# RWKV chunk A: prefetch block and next-chunk LDS staging interleaved into the recurrence body (quota 2,3,3,4 per step)
# speedup vs baseline: 1.1343x; 1.0023x over previous
.LBB0_334:
	v_lshlrev_b32_e32 v9, 16, v9
	v_mul_f32_e32 v9, 0x3fb8aa3b, v9
	v_lshlrev_b32_e32 v8, 16, v62
	v_lshlrev_b32_e32 v62, 16, v88
	v_lshlrev_b32_e32 v63, 16, v67
	v_exp_f32_e32 v9, v9
	v_lshlrev_b32_e32 v20, 16, v20
	v_sub_f32_e32 v63, v63, v62
	v_add_f32_e32 v67, -1.0, v20
	v_fma_f32 v63, v16, v63, v62
	v_fma_f32 v67, v19, v67, 1.0
	v_lshlrev_b32_e32 v65, 16, v68
	v_lshlrev_b32_e32 v66, 16, v66
	v_mul_f32_e32 v67, v67, v63
	v_sub_f32_e32 v66, v66, v65
	ds_write2st64_b32 v32, v9, v67 offset0:16 offset1:32
	v_mul_f32_e64 v9, v18, -v63
	v_fma_f32 v66, v17, v66, v65
	v_mul_f32_e32 v9, v21, v9
	v_lshlrev_b32_e32 v22, 16, v22
	v_lshlrev_b32_e32 v0, 16, v89
	ds_write2st64_b32 v32, v66, v9 offset0:48 offset1:64
	v_mul_f32_e64 v9, -v9, v20
	v_mul_f32_e32 v22, 0x3fb8aa3b, v22
	v_sub_f32_e32 v8, v8, v0
	ds_write_b32 v32, v9 offset:20480
	v_lshlrev_b32_e32 v9, 16, v61
	v_lshlrev_b32_e32 v20, 16, v57
	v_exp_f32_e32 v22, v22
	v_lshlrev_b32_e32 v23, 16, v23
	v_fma_f32 v8, v3, v8, v0
	v_lshlrev_b32_e32 v21, 16, v58
	v_sub_f32_e32 v0, v0, v9
	v_sub_f32_e32 v57, v62, v20
	v_add_f32_e32 v61, -1.0, v23
	v_fma_f32 v0, v3, v0, v9
	v_fma_f32 v57, v16, v57, v20
	v_sub_f32_e32 v58, v65, v21
	v_fma_f32 v61, v19, v61, 1.0
	v_fma_f32 v58, v17, v58, v21
	v_mul_f32_e32 v61, v61, v57
	ds_write2st64_b32 v32, v8, v0 offset1:1
	ds_write_b32 v33, v22 offset:256
	ds_write_b32 v34, v61 offset:256
	ds_write_b32 v35, v58 offset:256
	v_mul_f32_e64 v0, v18, -v57
	v_mul_f32_e32 v0, v24, v0
	ds_write_b32 v36, v0 offset:256
	v_mul_f32_e64 v0, -v0, v23
	v_lshlrev_b32_e32 v23, 16, v25
	v_mul_f32_e32 v23, 0x3fb8aa3b, v23
	ds_write_b32 v37, v0 offset:256
	v_lshlrev_b32_e32 v0, 16, v64
	v_lshlrev_b32_e32 v8, 16, v60
	v_exp_f32_e32 v23, v23
	v_lshlrev_b32_e32 v24, 16, v27
	v_lshlrev_b32_e32 v22, 16, v56
	v_sub_f32_e32 v9, v9, v0
	v_sub_f32_e32 v20, v20, v8
	v_add_f32_e32 v25, -1.0, v24
	v_fma_f32 v9, v3, v9, v0
	v_fma_f32 v20, v16, v20, v8
	v_sub_f32_e32 v21, v21, v22
	v_fma_f32 v25, v19, v25, 1.0
	v_fma_f32 v21, v17, v21, v22
	v_mul_f32_e32 v25, v25, v20
	ds_write_b32 v32, v9 offset:512
	ds_write_b32 v33, v23 offset:512
	ds_write_b32 v34, v25 offset:512
	ds_write_b32 v35, v21 offset:512
	v_mul_f32_e64 v9, v18, -v20
	v_mul_f32_e32 v9, v26, v9
	ds_write_b32 v36, v9 offset:512
	v_mul_f32_e64 v9, -v9, v24
	ds_write_b32 v37, v9 offset:512
	v_lshlrev_b32_e32 v9, 16, v55
	v_lshlrev_b32_e32 v20, 16, v59
	v_sub_f32_e32 v0, v0, v9
	v_lshlrev_b32_e32 v21, 16, v54
	v_fmac_f32_e32 v9, v3, v0
	v_sub_f32_e32 v0, v8, v20
	v_fmac_f32_e32 v20, v16, v0
	v_sub_f32_e32 v0, v22, v21
	v_fmac_f32_e32 v21, v17, v0
	v_lshlrev_b32_e32 v0, 16, v28
	v_mul_f32_e32 v0, 0x3fb8aa3b, v0
	v_exp_f32_e32 v0, v0
	v_lshlrev_b32_e32 v8, 16, v29
	v_add_f32_e32 v22, -1.0, v8
	v_fma_f32 v22, v19, v22, 1.0
	v_mul_f32_e32 v22, v22, v20
	ds_write_b32 v32, v9 offset:768
	ds_write_b32 v33, v0 offset:768
	ds_write_b32 v34, v22 offset:768
	ds_write_b32 v35, v21 offset:768
	v_mul_f32_e64 v0, v18, -v20
	v_mul_f32_e32 v0, v30, v0
	s_min_u32 s5, s4, 0xfd
	ds_write_b32 v36, v0 offset:768
	v_mul_f32_e64 v0, -v0, v8
	v_lshl_add_u32 v8, s5, 4, v38
	ds_write_b32 v37, v0 offset:768
	v_max_i32_e32 v0, 1, v8
	v_add_u32_e32 v0, -1, v0
	v_lshl_add_u64 v[20:21], s[56:57], 0, v[0:1]
	v_mad_u64_u32 v[22:23], s[6:7], v20, s29, v[4:5]
	v_max_i32_e32 v0, 0, v8
	v_mad_i32_i24 v23, v21, s29, v23
	v_lshl_add_u64 v[20:21], s[56:57], 0, v[0:1]
	v_max_i32_e32 v0, -1, v8
	s_waitcnt lgkmcnt(0)
	s_barrier
	ds_read_b128 v[220:223], v40 offset:16384
	ds_read_b128 v[236:239], v40 offset:8192
	ds_read2st64_b32 v[108:109], v39 offset0:0 offset1:1
	ds_read_b128 v[244:247], v40 offset:20480
	ds_read_b128 v[228:231], v40 offset:4096
	ds_read_b128 v[100:103], v40 offset:0
	ds_read_b128 v[224:227], v40 offset:16640
	ds_read_b128 v[240:243], v40 offset:8448
	ds_read2st64_b32 v[110:111], v39 offset0:2 offset1:3
	ds_read_b128 v[248:251], v40 offset:20736
	ds_read_b128 v[232:235], v40 offset:4352
	s_waitcnt lgkmcnt(6)
	v_pk_mul_f32 v[88:89], v[12:13], v[220:221]
	v_pk_fma_f32 v[88:89], v[10:11], v[222:223], v[88:89]
	v_add_f32_e32 v90, v88, v89
	global_load_ushort v55, v[22:23], off
	global_load_ushort v57, v[22:23], off offset:1024
	v_pk_mul_f32 v[92:93], v[108:109], v[236:237] op_sel_hi:[0,1]
	v_pk_mul_f32 v[94:95], v[108:109], v[238:239] op_sel_hi:[0,1]
	v_add_f32_dpp v90, v90, v90 row_ror:8 row_mask:0xf bank_mask:0xf bound_ctrl:1
	ds_read_b128 v[220:223], v40 offset:16896
	ds_read_b128 v[236:239], v40 offset:8704
	v_add_f32_dpp v90, v90, v90 row_ror:4 row_mask:0xf bank_mask:0xf bound_ctrl:1
	s_nop 1
	v_add_f32_dpp v90, v90, v90 row_ror:2 row_mask:0xf bank_mask:0xf bound_ctrl:1
	ds_read_b128 v[104:107], v40 offset:256
	s_nop 0
	v_add_f32_dpp v90, v90, v90 row_ror:1 row_mask:0xf bank_mask:0xf bound_ctrl:1
	global_load_ushort v54, v[22:23], off offset:2048
	v_mad_u64_u32 v[22:23], s[6:7], v20, s29, v[4:5]
	v_add_u32_e32 v0, 1, v0
	v_pk_fma_f32 v[92:93], v[90:91], v[244:245], v[92:93] op_sel_hi:[0,1,1]
	v_pk_fma_f32 v[94:95], v[90:91], v[246:247], v[94:95] op_sel_hi:[0,1,1]
	ds_read_b128 v[244:247], v40 offset:20992
	v_mad_i32_i24 v23, v21, s29, v23
	v_lshl_add_u64 v[20:21], s[56:57], 0, v[0:1]
	v_max_i32_e32 v0, -2, v8
	v_pk_fma_f32 v[12:13], v[12:13], v[228:229], v[92:93]
	v_pk_fma_f32 v[10:11], v[10:11], v[230:231], v[94:95]
	ds_read_b128 v[228:231], v40 offset:4608
	global_load_ushort v59, v[22:23], off
	global_load_ushort v60, v[22:23], off offset:1024
	global_load_ushort v56, v[22:23], off offset:2048
	v_mad_u64_u32 v[22:23], s[6:7], v20, s29, v[4:5]
	s_waitcnt lgkmcnt(5)
	v_pk_mul_f32 v[88:89], v[12:13], v[224:225]
	v_pk_fma_f32 v[88:89], v[10:11], v[226:227], v[88:89]
	v_add_f32_e32 v90, v88, v89
	v_add_u32_e32 v0, 2, v0
	v_mad_i32_i24 v23, v21, s29, v23
	v_pk_mul_f32 v[92:93], v[108:109], v[240:241] op_sel:[1,0] op_sel_hi:[1,1]
	v_pk_mul_f32 v[94:95], v[108:109], v[242:243] op_sel:[1,0] op_sel_hi:[1,1]
	v_add_f32_dpp v90, v90, v90 row_ror:8 row_mask:0xf bank_mask:0xf bound_ctrl:1
	ds_read_b128 v[224:227], v40 offset:17152
	ds_read_b128 v[240:243], v40 offset:8960
	v_add_f32_dpp v90, v90, v90 row_ror:4 row_mask:0xf bank_mask:0xf bound_ctrl:1
	v_pk_mul_f32 v[100:101], v[12:13], v[100:101]
	v_pk_fma_f32 v[100:101], v[10:11], v[102:103], v[100:101]
	v_add_f32_dpp v90, v90, v90 row_ror:2 row_mask:0xf bank_mask:0xf bound_ctrl:1
	v_add_f32_e32 v96, v100, v101
	ds_read_b128 v[100:103], v40 offset:512
	v_add_f32_dpp v90, v90, v90 row_ror:1 row_mask:0xf bank_mask:0xf bound_ctrl:1
	ds_read2st64_b32 v[108:109], v39 offset0:4 offset1:5
	v_lshl_add_u64 v[20:21], s[56:57], 0, v[0:1]
	v_max_i32_e32 v0, -3, v8
	global_load_ushort v61, v[22:23], off
	v_pk_fma_f32 v[92:93], v[90:91], v[248:249], v[92:93] op_sel_hi:[0,1,1]
	v_pk_fma_f32 v[94:95], v[90:91], v[250:251], v[94:95] op_sel_hi:[0,1,1]
	ds_read_b128 v[248:251], v40 offset:21248
	global_load_ushort v62, v[22:23], off offset:1024
	global_load_ushort v58, v[22:23], off offset:2048
	v_mad_u64_u32 v[22:23], s[6:7], v20, s29, v[4:5]
	v_pk_fma_f32 v[12:13], v[12:13], v[232:233], v[92:93]
	v_pk_fma_f32 v[10:11], v[10:11], v[234:235], v[94:95]
	ds_read_b128 v[232:235], v40 offset:4864
	v_add_u32_e32 v0, 3, v0
	v_mad_i32_i24 v23, v21, s29, v23
	v_lshl_add_u64 v[20:21], s[56:57], 0, v[0:1]
	v_ashrrev_i32_e32 v9, 31, v8
	s_waitcnt lgkmcnt(6)
	v_pk_mul_f32 v[88:89], v[12:13], v[220:221]
	v_pk_fma_f32 v[88:89], v[10:11], v[222:223], v[88:89]
	v_add_f32_e32 v90, v88, v89
	global_load_ushort v64, v[22:23], off
	global_load_ushort v67, v[22:23], off offset:1024
	v_pk_mul_f32 v[92:93], v[110:111], v[236:237] op_sel_hi:[0,1]
	v_pk_mul_f32 v[94:95], v[110:111], v[238:239] op_sel_hi:[0,1]
	v_add_f32_dpp v90, v90, v90 row_ror:8 row_mask:0xf bank_mask:0xf bound_ctrl:1
	ds_read_b128 v[220:223], v40 offset:17408
	ds_read_b128 v[236:239], v40 offset:9216
	v_add_f32_dpp v90, v90, v90 row_ror:4 row_mask:0xf bank_mask:0xf bound_ctrl:1
	v_pk_mul_f32 v[104:105], v[12:13], v[104:105]
	v_pk_fma_f32 v[104:105], v[10:11], v[106:107], v[104:105]
	v_add_f32_dpp v90, v90, v90 row_ror:2 row_mask:0xf bank_mask:0xf bound_ctrl:1
	v_add_f32_e32 v97, v104, v105
	ds_read_b128 v[104:107], v40 offset:768
	v_add_f32_dpp v90, v90, v90 row_ror:1 row_mask:0xf bank_mask:0xf bound_ctrl:1
	global_load_ushort v63, v[22:23], off offset:2048
	v_mad_u64_u32 v[22:23], s[6:7], v20, s29, v[4:5]
	v_lshl_add_u64 v[84:85], s[56:57], 0, v[8:9]
	v_pk_fma_f32 v[92:93], v[90:91], v[244:245], v[92:93] op_sel_hi:[0,1,1]
	v_pk_fma_f32 v[94:95], v[90:91], v[246:247], v[94:95] op_sel_hi:[0,1,1]
	ds_read_b128 v[244:247], v40 offset:21504
	v_mad_i32_i24 v23, v21, s29, v23
	v_lshlrev_b64 v[20:21], 10, v[84:85]
	v_lshlrev_b32_e32 v83, 1, v2
	v_pk_fma_f32 v[12:13], v[12:13], v[228:229], v[92:93]
	v_pk_fma_f32 v[10:11], v[10:11], v[230:231], v[94:95]
	ds_read_b128 v[228:231], v40 offset:5120
	v_or_b32_e32 v24, 1, v84
	v_mov_b32_e32 v25, v85
	v_or_b32_e32 v20, v20, v83
	v_lshlrev_b64 v[26:27], 10, v[24:25]
	s_waitcnt lgkmcnt(5)
	v_pk_mul_f32 v[88:89], v[12:13], v[224:225]
	v_pk_fma_f32 v[88:89], v[10:11], v[226:227], v[88:89]
	v_add_f32_e32 v90, v88, v89
	v_lshlrev_b64 v[24:25], 5, v[24:25]
	global_load_ushort v66, v[22:23], off
	v_pk_mul_f32 v[92:93], v[110:111], v[240:241] op_sel:[1,0] op_sel_hi:[1,1]
	v_pk_mul_f32 v[94:95], v[110:111], v[242:243] op_sel:[1,0] op_sel_hi:[1,1]
	v_add_f32_dpp v90, v90, v90 row_ror:8 row_mask:0xf bank_mask:0xf bound_ctrl:1
	ds_read_b128 v[224:227], v40 offset:17664
	ds_read_b128 v[240:243], v40 offset:9472
	v_add_f32_dpp v90, v90, v90 row_ror:4 row_mask:0xf bank_mask:0xf bound_ctrl:1
	v_pk_mul_f32 v[100:101], v[12:13], v[100:101]
	v_pk_fma_f32 v[100:101], v[10:11], v[102:103], v[100:101]
	v_add_f32_dpp v90, v90, v90 row_ror:2 row_mask:0xf bank_mask:0xf bound_ctrl:1
	v_add_f32_e32 v98, v100, v101
	ds_read_b128 v[100:103], v40 offset:1024
	v_add_f32_dpp v90, v90, v90 row_ror:1 row_mask:0xf bank_mask:0xf bound_ctrl:1
	ds_read2st64_b32 v[110:111], v39 offset0:6 offset1:7
	global_load_ushort v68, v[22:23], off offset:1024
	global_load_ushort v65, v[22:23], off offset:2048
	v_lshl_add_u64 v[22:23], s[0:1], 0, v[20:21]
	v_pk_fma_f32 v[92:93], v[90:91], v[248:249], v[92:93] op_sel_hi:[0,1,1]
	v_pk_fma_f32 v[94:95], v[90:91], v[250:251], v[94:95] op_sel_hi:[0,1,1]
	ds_read_b128 v[248:251], v40 offset:21760
	v_lshl_add_u64 v[20:21], s[24:25], 0, v[20:21]
	v_lshl_add_u64 v[24:25], s[58:59], 0, v[24:25]
	global_load_ushort v9, v[22:23], off
	v_pk_fma_f32 v[12:13], v[12:13], v[232:233], v[92:93]
	v_pk_fma_f32 v[10:11], v[10:11], v[234:235], v[94:95]
	ds_read_b128 v[232:235], v40 offset:5376
	v_or_b32_e32 v26, v26, v83
	global_load_dword v24, v[24:25], off
	v_or_b32_e32 v28, 2, v84
	global_load_ushort v20, v[20:21], off
	s_waitcnt lgkmcnt(6)
	v_pk_mul_f32 v[88:89], v[12:13], v[220:221]
	v_pk_fma_f32 v[88:89], v[10:11], v[222:223], v[88:89]
	v_add_f32_e32 v90, v88, v89
	v_lshlrev_b64 v[22:23], 5, v[84:85]
	v_lshl_add_u64 v[22:23], s[58:59], 0, v[22:23]
	v_pk_mul_f32 v[92:93], v[108:109], v[236:237] op_sel_hi:[0,1]
	v_pk_mul_f32 v[94:95], v[108:109], v[238:239] op_sel_hi:[0,1]
	v_add_f32_dpp v90, v90, v90 row_ror:8 row_mask:0xf bank_mask:0xf bound_ctrl:1
	ds_read_b128 v[220:223], v40 offset:17920
	ds_read_b128 v[236:239], v40 offset:9728
	v_add_f32_dpp v90, v90, v90 row_ror:4 row_mask:0xf bank_mask:0xf bound_ctrl:1
	v_pk_mul_f32 v[104:105], v[12:13], v[104:105]
	v_pk_fma_f32 v[104:105], v[10:11], v[106:107], v[104:105]
	v_add_f32_dpp v90, v90, v90 row_ror:2 row_mask:0xf bank_mask:0xf bound_ctrl:1
	v_add_f32_e32 v99, v104, v105
	ds_read_b128 v[104:107], v40 offset:1280
	v_add_f32_dpp v90, v90, v90 row_ror:1 row_mask:0xf bank_mask:0xf bound_ctrl:1
	global_load_dword v21, v[22:23], off
	v_lshl_add_u64 v[22:23], s[0:1], 0, v[26:27]
	v_lshl_add_u64 v[26:27], s[24:25], 0, v[26:27]
	v_pk_fma_f32 v[92:93], v[90:91], v[244:245], v[92:93] op_sel_hi:[0,1,1]
	v_pk_fma_f32 v[94:95], v[90:91], v[246:247], v[94:95] op_sel_hi:[0,1,1]
	ds_read_b128 v[244:247], v40 offset:22016
	v_mov_b32_e32 v29, v85
	global_load_ushort v22, v[22:23], off
	v_or_b32_e32 v84, 3, v84
	v_pk_fma_f32 v[12:13], v[12:13], v[228:229], v[92:93]
	v_pk_fma_f32 v[10:11], v[10:11], v[230:231], v[94:95]
	ds_read_b128 v[228:231], v40 offset:5632
	global_load_ushort v23, v[26:27], off
	v_lshlrev_b64 v[26:27], 10, v[28:29]
	v_or_b32_e32 v26, v26, v83
	v_lshl_add_u64 v[86:87], s[0:1], 0, v[26:27]
	s_waitcnt lgkmcnt(5)
	v_pk_mul_f32 v[88:89], v[12:13], v[224:225]
	v_pk_fma_f32 v[88:89], v[10:11], v[226:227], v[88:89]
	v_add_f32_e32 v90, v88, v89
	global_load_ushort v25, v[86:87], off
	v_lshlrev_b64 v[28:29], 5, v[28:29]
	v_pk_mul_f32 v[92:93], v[108:109], v[240:241] op_sel:[1,0] op_sel_hi:[1,1]
	v_pk_mul_f32 v[94:95], v[108:109], v[242:243] op_sel:[1,0] op_sel_hi:[1,1]
	v_add_f32_dpp v90, v90, v90 row_ror:8 row_mask:0xf bank_mask:0xf bound_ctrl:1
	ds_read_b128 v[224:227], v40 offset:18176
	ds_read_b128 v[240:243], v40 offset:9984
	v_add_f32_dpp v90, v90, v90 row_ror:4 row_mask:0xf bank_mask:0xf bound_ctrl:1
	v_pk_mul_f32 v[100:101], v[12:13], v[100:101]
	v_pk_fma_f32 v[100:101], v[10:11], v[102:103], v[100:101]
	v_add_f32_dpp v90, v90, v90 row_ror:2 row_mask:0xf bank_mask:0xf bound_ctrl:1
	v_add_f32_e32 v116, v100, v101
	ds_read_b128 v[100:103], v40 offset:1536
	v_add_f32_dpp v90, v90, v90 row_ror:1 row_mask:0xf bank_mask:0xf bound_ctrl:1
	ds_read2st64_b32 v[108:109], v39 offset0:8 offset1:9
	v_lshlrev_b64 v[86:87], 10, v[84:85]
	v_lshlrev_b64 v[84:85], 5, v[84:85]
	v_lshl_add_u64 v[26:27], s[24:25], 0, v[26:27]
	v_pk_fma_f32 v[92:93], v[90:91], v[248:249], v[92:93] op_sel_hi:[0,1,1]
	v_pk_fma_f32 v[94:95], v[90:91], v[250:251], v[94:95] op_sel_hi:[0,1,1]
	ds_read_b128 v[248:251], v40 offset:22272
	v_lshl_add_u64 v[28:29], s[58:59], 0, v[28:29]
	v_or_b32_e32 v86, v86, v83
	v_lshl_add_u64 v[84:85], s[58:59], 0, v[84:85]
	v_pk_fma_f32 v[12:13], v[12:13], v[232:233], v[92:93]
	v_pk_fma_f32 v[10:11], v[10:11], v[234:235], v[94:95]
	ds_read_b128 v[232:235], v40 offset:5888
	global_load_ushort v27, v[26:27], off
	v_mov_b32_e32 v0, v31
	global_load_dword v30, v[84:85], off
	global_load_dword v26, v[28:29], off
	s_waitcnt lgkmcnt(6)
	v_pk_mul_f32 v[88:89], v[12:13], v[220:221]
	v_pk_fma_f32 v[88:89], v[10:11], v[222:223], v[88:89]
	v_add_f32_e32 v90, v88, v89
	v_lshl_add_u64 v[28:29], s[0:1], 0, v[86:87]
	v_lshl_add_u64 v[86:87], s[24:25], 0, v[86:87]
	v_pk_mul_f32 v[92:93], v[110:111], v[236:237] op_sel_hi:[0,1]
	v_pk_mul_f32 v[94:95], v[110:111], v[238:239] op_sel_hi:[0,1]
	v_add_f32_dpp v90, v90, v90 row_ror:8 row_mask:0xf bank_mask:0xf bound_ctrl:1
	ds_read_b128 v[220:223], v40 offset:18432
	ds_read_b128 v[236:239], v40 offset:10240
	v_add_f32_dpp v90, v90, v90 row_ror:4 row_mask:0xf bank_mask:0xf bound_ctrl:1
	v_pk_mul_f32 v[104:105], v[12:13], v[104:105]
	v_pk_fma_f32 v[104:105], v[10:11], v[106:107], v[104:105]
	v_add_f32_dpp v90, v90, v90 row_ror:2 row_mask:0xf bank_mask:0xf bound_ctrl:1
	v_add_f32_e32 v217, v104, v105
	ds_read_b128 v[104:107], v40 offset:1792
	v_add_f32_dpp v90, v90, v90 row_ror:1 row_mask:0xf bank_mask:0xf bound_ctrl:1
	global_load_ushort v28, v[28:29], off
	v_mov_b32_e32 v84, v40
	global_load_ushort v29, v[86:87], off
	v_pk_fma_f32 v[92:93], v[90:91], v[244:245], v[92:93] op_sel_hi:[0,1,1]
	v_pk_fma_f32 v[94:95], v[90:91], v[246:247], v[94:95] op_sel_hi:[0,1,1]
	ds_read_b128 v[244:247], v40 offset:22528
	v_mov_b32_e32 v86, 0
	v_mov_b32_e32 v85, v39
	s_mov_b32 s5, 0
	v_pk_fma_f32 v[12:13], v[12:13], v[228:229], v[92:93]
	v_pk_fma_f32 v[10:11], v[10:11], v[230:231], v[94:95]
	ds_read_b128 v[228:231], v40 offset:6144
	s_waitcnt vmcnt(38)
	v_lshlrev_b32_e32 v15, 16, v15
	v_mul_f32_e32 v15, 0x3fb8aa3b, v15
	v_lshlrev_b32_e32 v75, 16, v75
	v_lshlrev_b32_e32 v78, 16, v78
	s_waitcnt lgkmcnt(5)
	v_pk_mul_f32 v[88:89], v[12:13], v[224:225]
	v_pk_fma_f32 v[88:89], v[10:11], v[226:227], v[88:89]
	v_add_f32_e32 v90, v88, v89
	v_exp_f32_e32 v15, v15
	s_waitcnt vmcnt(37)
	v_lshlrev_b32_e32 v43, 16, v43
	v_pk_mul_f32 v[92:93], v[110:111], v[240:241] op_sel:[1,0] op_sel_hi:[1,1]
	v_pk_mul_f32 v[94:95], v[110:111], v[242:243] op_sel:[1,0] op_sel_hi:[1,1]
	v_add_f32_dpp v90, v90, v90 row_ror:8 row_mask:0xf bank_mask:0xf bound_ctrl:1
	ds_read_b128 v[224:227], v40 offset:18688
	ds_read_b128 v[240:243], v40 offset:10496
	v_add_f32_dpp v90, v90, v90 row_ror:4 row_mask:0xf bank_mask:0xf bound_ctrl:1
	v_pk_mul_f32 v[100:101], v[12:13], v[100:101]
	v_pk_fma_f32 v[100:101], v[10:11], v[102:103], v[100:101]
	v_add_f32_dpp v90, v90, v90 row_ror:2 row_mask:0xf bank_mask:0xf bound_ctrl:1
	v_add_f32_e32 v218, v100, v101
	ds_read_b128 v[100:103], v40 offset:2048
	v_add_f32_dpp v90, v90, v90 row_ror:1 row_mask:0xf bank_mask:0xf bound_ctrl:1
	ds_read2st64_b32 v[110:111], v39 offset0:10 offset1:11
	v_sub_f32_e32 v78, v78, v75
	v_add_f32_e32 v84, -1.0, v43
	v_lshlrev_b32_e32 v81, 16, v81
	v_pk_fma_f32 v[92:93], v[90:91], v[248:249], v[92:93] op_sel_hi:[0,1,1]
	v_pk_fma_f32 v[94:95], v[90:91], v[250:251], v[94:95] op_sel_hi:[0,1,1]
	ds_read_b128 v[248:251], v40 offset:22784
	v_lshlrev_b32_e32 v79, 16, v79
	v_fma_f32 v78, v16, v78, v75
	v_fma_f32 v84, v19, v84, 1.0
	v_pk_fma_f32 v[12:13], v[12:13], v[232:233], v[92:93]
	v_pk_fma_f32 v[10:11], v[10:11], v[234:235], v[94:95]
	ds_read_b128 v[232:235], v40 offset:6400
	v_lshlrev_b32_e32 v0, 16, v82
	v_sub_f32_e32 v79, v79, v81
	v_mul_f32_e32 v82, v18, v78
	v_mul_f32_e32 v78, v78, v84
	s_waitcnt lgkmcnt(6)
	v_pk_mul_f32 v[88:89], v[12:13], v[220:221]
	v_pk_fma_f32 v[88:89], v[10:11], v[222:223], v[88:89]
	v_add_f32_e32 v90, v88, v89
	v_fma_f32 v79, v17, v79, v81
	ds_write2st64_b32 v32, v15, v78 offset0:112 offset1:128
	v_pk_mul_f32 v[92:93], v[108:109], v[236:237] op_sel_hi:[0,1]
	v_pk_mul_f32 v[94:95], v[108:109], v[238:239] op_sel_hi:[0,1]
	v_add_f32_dpp v90, v90, v90 row_ror:8 row_mask:0xf bank_mask:0xf bound_ctrl:1
	ds_read_b128 v[220:223], v40 offset:18944
	ds_read_b128 v[236:239], v40 offset:10752
	v_add_f32_dpp v90, v90, v90 row_ror:4 row_mask:0xf bank_mask:0xf bound_ctrl:1
	v_pk_mul_f32 v[104:105], v[12:13], v[104:105]
	v_pk_fma_f32 v[104:105], v[10:11], v[106:107], v[104:105]
	v_add_f32_dpp v90, v90, v90 row_ror:2 row_mask:0xf bank_mask:0xf bound_ctrl:1
	v_add_f32_e32 v219, v104, v105
	ds_read_b128 v[104:107], v40 offset:2304
	v_add_f32_dpp v90, v90, v90 row_ror:1 row_mask:0xf bank_mask:0xf bound_ctrl:1
	s_waitcnt vmcnt(36)
	v_mul_f32_e64 v15, v82, -v44
	s_waitcnt vmcnt(35)
	v_lshlrev_b32_e32 v48, 16, v48
	v_lshlrev_b32_e32 v80, 16, v80
	v_pk_fma_f32 v[92:93], v[90:91], v[244:245], v[92:93] op_sel_hi:[0,1,1]
	v_pk_fma_f32 v[94:95], v[90:91], v[246:247], v[94:95] op_sel_hi:[0,1,1]
	ds_read_b128 v[244:247], v40 offset:23040
	ds_write2st64_b32 v32, v79, v15 offset0:144 offset1:160
	v_mul_f32_e64 v15, -v15, v43
	v_lshlrev_b32_e32 v43, 16, v74
	v_pk_fma_f32 v[12:13], v[12:13], v[228:229], v[92:93]
	v_pk_fma_f32 v[10:11], v[10:11], v[230:231], v[94:95]
	ds_read_b128 v[228:231], v40 offset:6656
	v_mul_f32_e32 v48, 0x3fb8aa3b, v48
	v_sub_f32_e32 v80, v80, v0
	ds_write_b32 v32, v15 offset:45056
	v_lshlrev_b32_e32 v15, 16, v76
	s_waitcnt lgkmcnt(8)
	v_pk_mul_f32 v[88:89], v[12:13], v[224:225]
	v_pk_fma_f32 v[88:89], v[10:11], v[226:227], v[88:89]
	v_add_f32_e32 v90, v88, v89
	v_sub_f32_e32 v74, v75, v43
	v_exp_f32_e32 v48, v48
	v_pk_mul_f32 v[92:93], v[108:109], v[240:241] op_sel:[1,0] op_sel_hi:[1,1]
	v_pk_mul_f32 v[94:95], v[108:109], v[242:243] op_sel:[1,0] op_sel_hi:[1,1]
	v_add_f32_dpp v90, v90, v90 row_ror:8 row_mask:0xf bank_mask:0xf bound_ctrl:1
	ds_read_b128 v[224:227], v40 offset:19200
	ds_read_b128 v[240:243], v40 offset:11008
	v_add_f32_dpp v90, v90, v90 row_ror:4 row_mask:0xf bank_mask:0xf bound_ctrl:1
	v_pk_mul_f32 v[100:101], v[12:13], v[100:101]
	v_pk_fma_f32 v[100:101], v[10:11], v[102:103], v[100:101]
	v_add_f32_dpp v90, v90, v90 row_ror:2 row_mask:0xf bank_mask:0xf bound_ctrl:1
	v_add_f32_e32 v187, v100, v101
	ds_read_b128 v[100:103], v40 offset:2560
	v_add_f32_dpp v90, v90, v90 row_ror:1 row_mask:0xf bank_mask:0xf bound_ctrl:1
	ds_read2st64_b32 v[108:109], v39 offset0:12 offset1:13
	s_waitcnt vmcnt(34)
	v_lshlrev_b32_e32 v49, 16, v49
	v_fma_f32 v80, v3, v80, v0
	v_lshlrev_b32_e32 v44, 16, v77
	v_pk_fma_f32 v[92:93], v[90:91], v[248:249], v[92:93] op_sel_hi:[0,1,1]
	v_pk_fma_f32 v[94:95], v[90:91], v[250:251], v[94:95] op_sel_hi:[0,1,1]
	ds_read_b128 v[248:251], v40 offset:23296
	v_sub_f32_e32 v0, v0, v15
	v_fma_f32 v74, v16, v74, v43
	v_add_f32_e32 v77, -1.0, v49
	v_pk_fma_f32 v[12:13], v[12:13], v[232:233], v[92:93]
	v_pk_fma_f32 v[10:11], v[10:11], v[234:235], v[94:95]
	ds_read_b128 v[232:235], v40 offset:6912
	v_fma_f32 v0, v3, v0, v15
	v_sub_f32_e32 v75, v81, v44
	v_mul_f32_e32 v76, v18, v74
	v_fma_f32 v77, v19, v77, 1.0
	s_waitcnt lgkmcnt(7)
	v_pk_mul_f32 v[88:89], v[12:13], v[220:221]
	v_pk_fma_f32 v[88:89], v[10:11], v[222:223], v[88:89]
	v_add_f32_e32 v90, v88, v89
	v_fma_f32 v75, v17, v75, v44
	v_mul_f32_e32 v74, v74, v77
	v_pk_mul_f32 v[92:93], v[110:111], v[236:237] op_sel_hi:[0,1]
	v_pk_mul_f32 v[94:95], v[110:111], v[238:239] op_sel_hi:[0,1]
	v_add_f32_dpp v90, v90, v90 row_ror:8 row_mask:0xf bank_mask:0xf bound_ctrl:1
	ds_read_b128 v[220:223], v40 offset:19456
	ds_read_b128 v[236:239], v40 offset:11264
	v_add_f32_dpp v90, v90, v90 row_ror:4 row_mask:0xf bank_mask:0xf bound_ctrl:1
	v_pk_mul_f32 v[104:105], v[12:13], v[104:105]
	v_pk_fma_f32 v[104:105], v[10:11], v[106:107], v[104:105]
	v_add_f32_dpp v90, v90, v90 row_ror:2 row_mask:0xf bank_mask:0xf bound_ctrl:1
	v_add_f32_e32 v190, v104, v105
	ds_read_b128 v[104:107], v40 offset:2816
	v_add_f32_dpp v90, v90, v90 row_ror:1 row_mask:0xf bank_mask:0xf bound_ctrl:1
	ds_write2st64_b32 v32, v80, v0 offset0:96 offset1:97
	ds_write_b32 v33, v48 offset:24832
	ds_write_b32 v34, v74 offset:24832
	v_pk_fma_f32 v[92:93], v[90:91], v[244:245], v[92:93] op_sel_hi:[0,1,1]
	v_pk_fma_f32 v[94:95], v[90:91], v[246:247], v[94:95] op_sel_hi:[0,1,1]
	ds_read_b128 v[244:247], v40 offset:23552
	ds_write_b32 v35, v75 offset:24832
	s_waitcnt vmcnt(33)
	v_mul_f32_e64 v0, v76, -v46
	s_waitcnt vmcnt(32)
	v_lshlrev_b32_e32 v45, 16, v45
	v_pk_fma_f32 v[12:13], v[12:13], v[228:229], v[92:93]
	v_pk_fma_f32 v[10:11], v[10:11], v[230:231], v[94:95]
	ds_read_b128 v[228:231], v40 offset:7168
	ds_write_b32 v36, v0 offset:24832
	v_mul_f32_e64 v0, -v0, v49
	v_lshlrev_b32_e32 v46, 16, v69
	v_mul_f32_e32 v45, 0x3fb8aa3b, v45
	s_waitcnt lgkmcnt(10)
	v_pk_mul_f32 v[88:89], v[12:13], v[224:225]
	v_pk_fma_f32 v[88:89], v[10:11], v[226:227], v[88:89]
	v_add_f32_e32 v90, v88, v89
	ds_write_b32 v37, v0 offset:24832
	v_lshlrev_b32_e32 v0, 16, v72
	v_pk_mul_f32 v[92:93], v[110:111], v[240:241] op_sel:[1,0] op_sel_hi:[1,1]
	v_pk_mul_f32 v[94:95], v[110:111], v[242:243] op_sel:[1,0] op_sel_hi:[1,1]
	v_add_f32_dpp v90, v90, v90 row_ror:8 row_mask:0xf bank_mask:0xf bound_ctrl:1
	ds_read_b128 v[224:227], v40 offset:19712
	ds_read_b128 v[240:243], v40 offset:11520
	v_add_f32_dpp v90, v90, v90 row_ror:4 row_mask:0xf bank_mask:0xf bound_ctrl:1
	v_pk_mul_f32 v[100:101], v[12:13], v[100:101]
	v_pk_fma_f32 v[100:101], v[10:11], v[102:103], v[100:101]
	v_add_f32_dpp v90, v90, v90 row_ror:2 row_mask:0xf bank_mask:0xf bound_ctrl:1
	v_add_f32_e32 v191, v100, v101
	ds_read_b128 v[100:103], v40 offset:3072
	v_add_f32_dpp v90, v90, v90 row_ror:1 row_mask:0xf bank_mask:0xf bound_ctrl:1
	ds_read2st64_b32 v[110:111], v39 offset0:14 offset1:15
	v_sub_f32_e32 v43, v43, v46
	v_exp_f32_e32 v45, v45
	s_waitcnt vmcnt(31)
	v_lshlrev_b32_e32 v47, 16, v47
	v_pk_fma_f32 v[92:93], v[90:91], v[248:249], v[92:93] op_sel_hi:[0,1,1]
	v_pk_fma_f32 v[94:95], v[90:91], v[250:251], v[94:95] op_sel_hi:[0,1,1]
	ds_read_b128 v[248:251], v40 offset:23808
	v_lshlrev_b32_e32 v48, 16, v73
	v_sub_f32_e32 v15, v15, v0
	v_fma_f32 v43, v16, v43, v46
	v_pk_fma_f32 v[12:13], v[12:13], v[232:233], v[92:93]
	v_pk_fma_f32 v[10:11], v[10:11], v[234:235], v[94:95]
	ds_read_b128 v[232:235], v40 offset:7424
	v_add_f32_e32 v69, -1.0, v47
	v_fma_f32 v15, v3, v15, v0
	v_sub_f32_e32 v44, v44, v48
	v_mul_f32_e32 v49, v18, v43
	s_waitcnt lgkmcnt(8)
	v_pk_mul_f32 v[88:89], v[12:13], v[220:221]
	v_pk_fma_f32 v[88:89], v[10:11], v[222:223], v[88:89]
	v_add_f32_e32 v90, v88, v89
	v_fma_f32 v69, v19, v69, 1.0
	v_fma_f32 v44, v17, v44, v48
	v_pk_mul_f32 v[92:93], v[108:109], v[236:237] op_sel_hi:[0,1]
	v_pk_mul_f32 v[94:95], v[108:109], v[238:239] op_sel_hi:[0,1]
	v_add_f32_dpp v90, v90, v90 row_ror:8 row_mask:0xf bank_mask:0xf bound_ctrl:1
	ds_read_b128 v[220:223], v40 offset:19968
	ds_read_b128 v[236:239], v40 offset:11776
	v_add_f32_dpp v90, v90, v90 row_ror:4 row_mask:0xf bank_mask:0xf bound_ctrl:1
	v_pk_mul_f32 v[104:105], v[12:13], v[104:105]
	v_pk_fma_f32 v[104:105], v[10:11], v[106:107], v[104:105]
	v_add_f32_dpp v90, v90, v90 row_ror:2 row_mask:0xf bank_mask:0xf bound_ctrl:1
	v_add_f32_e32 v200, v104, v105
	ds_read_b128 v[104:107], v40 offset:3328
	v_add_f32_dpp v90, v90, v90 row_ror:1 row_mask:0xf bank_mask:0xf bound_ctrl:1
	v_mul_f32_e32 v43, v43, v69
	ds_write_b32 v32, v15 offset:25088
	ds_write_b32 v33, v45 offset:25088
	v_pk_fma_f32 v[92:93], v[90:91], v[244:245], v[92:93] op_sel_hi:[0,1,1]
	v_pk_fma_f32 v[94:95], v[90:91], v[246:247], v[94:95] op_sel_hi:[0,1,1]
	ds_read_b128 v[244:247], v40 offset:24064
	ds_write_b32 v34, v43 offset:25088
	ds_write_b32 v35, v44 offset:25088
	s_waitcnt vmcnt(30)
	v_mul_f32_e64 v15, v49, -v52
	v_pk_fma_f32 v[12:13], v[12:13], v[228:229], v[92:93]
	v_pk_fma_f32 v[10:11], v[10:11], v[230:231], v[94:95]
	ds_read_b128 v[228:231], v40 offset:7680
	ds_write_b32 v36, v15 offset:25088
	v_mul_f32_e64 v15, -v15, v47
	ds_write_b32 v37, v15 offset:25088
	v_lshlrev_b32_e32 v15, 16, v70
	s_waitcnt lgkmcnt(11)
	v_pk_mul_f32 v[88:89], v[12:13], v[224:225]
	v_pk_fma_f32 v[88:89], v[10:11], v[226:227], v[88:89]
	v_add_f32_e32 v90, v88, v89
	v_lshlrev_b32_e32 v14, 16, v14
	v_sub_f32_e32 v0, v0, v15
	v_pk_mul_f32 v[92:93], v[108:109], v[240:241] op_sel:[1,0] op_sel_hi:[1,1]
	v_pk_mul_f32 v[94:95], v[108:109], v[242:243] op_sel:[1,0] op_sel_hi:[1,1]
	v_add_f32_dpp v90, v90, v90 row_ror:8 row_mask:0xf bank_mask:0xf bound_ctrl:1
	ds_read_b128 v[224:227], v40 offset:20224
	ds_read_b128 v[240:243], v40 offset:12032
	v_add_f32_dpp v90, v90, v90 row_ror:4 row_mask:0xf bank_mask:0xf bound_ctrl:1
	v_pk_mul_f32 v[100:101], v[12:13], v[100:101]
	v_pk_fma_f32 v[100:101], v[10:11], v[102:103], v[100:101]
	v_add_f32_dpp v90, v90, v90 row_ror:2 row_mask:0xf bank_mask:0xf bound_ctrl:1
	v_add_f32_e32 v112, v100, v101
	ds_read_b128 v[100:103], v40 offset:3584
	v_add_f32_dpp v90, v90, v90 row_ror:1 row_mask:0xf bank_mask:0xf bound_ctrl:1
	v_lshlrev_b32_e32 v43, 16, v71
	v_fmac_f32_e32 v15, v3, v0
	v_sub_f32_e32 v0, v46, v14
	v_pk_fma_f32 v[92:93], v[90:91], v[248:249], v[92:93] op_sel_hi:[0,1,1]
	v_pk_fma_f32 v[94:95], v[90:91], v[250:251], v[94:95] op_sel_hi:[0,1,1]
	ds_read_b128 v[248:251], v40 offset:24320
	v_fmac_f32_e32 v14, v16, v0
	v_sub_f32_e32 v0, v48, v43
	v_fmac_f32_e32 v43, v17, v0
	v_pk_fma_f32 v[12:13], v[12:13], v[232:233], v[92:93]
	v_pk_fma_f32 v[10:11], v[10:11], v[234:235], v[94:95]
	ds_read_b128 v[232:235], v40 offset:7936
	s_waitcnt vmcnt(29)
	v_lshlrev_b32_e32 v0, 16, v50
	v_mul_f32_e32 v0, 0x3fb8aa3b, v0
	v_exp_f32_e32 v0, v0
	s_waitcnt vmcnt(28)
	v_lshlrev_b32_e32 v44, 16, v51
	s_waitcnt lgkmcnt(7)
	v_pk_mul_f32 v[88:89], v[12:13], v[220:221]
	v_pk_fma_f32 v[88:89], v[10:11], v[222:223], v[88:89]
	v_add_f32_e32 v90, v88, v89
	v_add_f32_e32 v46, -1.0, v44
	s_or_b32 s5, s4, 1
	v_pk_mul_f32 v[92:93], v[110:111], v[236:237] op_sel_hi:[0,1]
	v_pk_mul_f32 v[94:95], v[110:111], v[238:239] op_sel_hi:[0,1]
	v_add_f32_dpp v90, v90, v90 row_ror:8 row_mask:0xf bank_mask:0xf bound_ctrl:1
	s_nop 1
	v_add_f32_dpp v90, v90, v90 row_ror:4 row_mask:0xf bank_mask:0xf bound_ctrl:1
	v_pk_mul_f32 v[104:105], v[12:13], v[104:105]
	v_pk_fma_f32 v[104:105], v[10:11], v[106:107], v[104:105]
	v_add_f32_dpp v90, v90, v90 row_ror:2 row_mask:0xf bank_mask:0xf bound_ctrl:1
	v_add_f32_e32 v113, v104, v105
	ds_read_b128 v[104:107], v40 offset:3840
	v_add_f32_dpp v90, v90, v90 row_ror:1 row_mask:0xf bank_mask:0xf bound_ctrl:1
	v_mul_f32_e32 v45, v18, v14
	v_fma_f32 v46, v19, v46, 1.0
	v_mul_f32_e32 v14, v14, v46
	v_pk_fma_f32 v[92:93], v[90:91], v[244:245], v[92:93] op_sel_hi:[0,1,1]
	v_pk_fma_f32 v[94:95], v[90:91], v[246:247], v[94:95] op_sel_hi:[0,1,1]
	ds_write_b32 v32, v15 offset:25344
	ds_write_b32 v33, v0 offset:25344
	ds_write_b32 v34, v14 offset:25344
	v_pk_fma_f32 v[12:13], v[12:13], v[228:229], v[92:93]
	v_pk_fma_f32 v[10:11], v[10:11], v[230:231], v[94:95]
	ds_write_b32 v35, v43 offset:25344
	s_waitcnt vmcnt(27)
	v_mul_f32_e64 v0, v45, -v53
	s_min_u32 s6, s5, 0xfd
	ds_write_b32 v36, v0 offset:25344
	s_waitcnt lgkmcnt(6)
	v_pk_mul_f32 v[88:89], v[12:13], v[224:225]
	v_pk_fma_f32 v[88:89], v[10:11], v[226:227], v[88:89]
	v_add_f32_e32 v90, v88, v89
	v_mul_f32_e64 v0, -v0, v44
	v_lshl_add_u32 v14, s6, 4, v38
	v_pk_mul_f32 v[92:93], v[110:111], v[240:241] op_sel:[1,0] op_sel_hi:[1,1]
	v_pk_mul_f32 v[94:95], v[110:111], v[242:243] op_sel:[1,0] op_sel_hi:[1,1]
	v_add_f32_dpp v90, v90, v90 row_ror:8 row_mask:0xf bank_mask:0xf bound_ctrl:1
	s_nop 1
	v_add_f32_dpp v90, v90, v90 row_ror:4 row_mask:0xf bank_mask:0xf bound_ctrl:1
	v_pk_mul_f32 v[100:101], v[12:13], v[100:101]
	v_pk_fma_f32 v[100:101], v[10:11], v[102:103], v[100:101]
	v_add_f32_dpp v90, v90, v90 row_ror:2 row_mask:0xf bank_mask:0xf bound_ctrl:1
	v_add_f32_e32 v114, v100, v101
	s_nop 0
	v_add_f32_dpp v90, v90, v90 row_ror:1 row_mask:0xf bank_mask:0xf bound_ctrl:1
	ds_write_b32 v37, v0 offset:25344
	v_max_i32_e32 v0, 1, v14
	v_add_u32_e32 v0, -1, v0
	v_pk_fma_f32 v[92:93], v[90:91], v[248:249], v[92:93] op_sel_hi:[0,1,1]
	v_pk_fma_f32 v[94:95], v[90:91], v[250:251], v[94:95] op_sel_hi:[0,1,1]
	v_lshl_add_u64 v[44:45], s[56:57], 0, v[0:1]
	v_mad_u64_u32 v[46:47], s[6:7], v44, s29, v[4:5]
	v_max_i32_e32 v0, 0, v14
	v_pk_fma_f32 v[12:13], v[12:13], v[232:233], v[92:93]
	v_pk_fma_f32 v[10:11], v[10:11], v[234:235], v[94:95]
	v_mad_i32_i24 v47, v45, s29, v47
	v_lshl_add_u64 v[44:45], s[56:57], 0, v[0:1]
	v_max_i32_e32 v0, -1, v14
	s_waitcnt lgkmcnt(6)
	v_pk_mul_f32 v[104:105], v[12:13], v[104:105]
	v_pk_fma_f32 v[104:105], v[10:11], v[106:107], v[104:105]
	v_add_f32_dpp v96, v96, v96 row_mirror row_mask:0xf bank_mask:0x3
	v_add_f32_dpp v96, v187, v187 row_mirror row_mask:0xf bank_mask:0xc
	v_add_f32_e32 v115, v104, v105
	v_add_f32_dpp v97, v97, v97 row_mirror row_mask:0xf bank_mask:0x3
	v_add_f32_dpp v97, v190, v190 row_mirror row_mask:0xf bank_mask:0xc
	v_add_f32_dpp v98, v98, v98 row_mirror row_mask:0xf bank_mask:0x3
	v_add_f32_dpp v98, v191, v191 row_mirror row_mask:0xf bank_mask:0xc
	v_add_f32_dpp v99, v99, v99 row_mirror row_mask:0xf bank_mask:0x3
	v_add_f32_dpp v99, v200, v200 row_mirror row_mask:0xf bank_mask:0xc
	v_add_f32_dpp v116, v116, v116 row_mirror row_mask:0xf bank_mask:0x3
	v_add_f32_dpp v116, v112, v112 row_mirror row_mask:0xf bank_mask:0xc
	v_add_f32_dpp v217, v217, v217 row_mirror row_mask:0xf bank_mask:0x3
	v_add_f32_dpp v217, v113, v113 row_mirror row_mask:0xf bank_mask:0xc
	v_add_f32_dpp v218, v218, v218 row_mirror row_mask:0xf bank_mask:0x3
	v_add_f32_dpp v218, v114, v114 row_mirror row_mask:0xf bank_mask:0xc
	v_add_f32_dpp v219, v219, v219 row_mirror row_mask:0xf bank_mask:0x3
	v_add_f32_dpp v219, v115, v115 row_mirror row_mask:0xf bank_mask:0xc
	v_add_f32_dpp v96, v96, v96 row_half_mirror row_mask:0xf bank_mask:0x5
	v_add_f32_dpp v96, v116, v116 row_half_mirror row_mask:0xf bank_mask:0xa
	v_add_f32_dpp v97, v97, v97 row_half_mirror row_mask:0xf bank_mask:0x5
	v_add_f32_dpp v97, v217, v217 row_half_mirror row_mask:0xf bank_mask:0xa
	v_add_f32_dpp v98, v98, v98 row_half_mirror row_mask:0xf bank_mask:0x5
	v_add_f32_dpp v98, v218, v218 row_half_mirror row_mask:0xf bank_mask:0xa
	v_add_f32_dpp v99, v99, v99 row_half_mirror row_mask:0xf bank_mask:0x5
	v_add_f32_dpp v99, v219, v219 row_half_mirror row_mask:0xf bank_mask:0xa
	s_mov_b32 vcc_lo, 0xcccccccc
	s_mov_b32 vcc_hi, 0xcccccccc
	v_cndmask_b32_e32 v187, v96, v98, vcc
	v_cndmask_b32_e32 v190, v98, v96, vcc
	v_cndmask_b32_e32 v200, v99, v97, vcc
	v_cndmask_b32_e32 v191, v97, v99, vcc
	v_add_f32_dpp v112, v190, v187 quad_perm:[2,3,0,1] row_mask:0xf bank_mask:0xf bound_ctrl:1
	v_add_f32_dpp v113, v200, v191 quad_perm:[2,3,0,1] row_mask:0xf bank_mask:0xf bound_ctrl:1
	s_mov_b32 vcc_lo, 0xaaaaaaaa
	s_mov_b32 vcc_hi, 0xaaaaaaaa
	v_cndmask_b32_e32 v114, v112, v113, vcc
	v_cndmask_b32_e32 v115, v113, v112, vcc
	s_nop 1
	v_add_f32_dpp v86, v115, v114 quad_perm:[1,0,3,2] row_mask:0xf bank_mask:0xf bound_ctrl:1
	v_lshl_or_b32 v114, s4, 4, v31
	v_or_b32_e32 v114, s56, v114
	v_mov_b32_e32 v115, s57
	v_lshlrev_b64 v[114:115], 10, v[114:115]
	v_cvt_pk_bf16_f32 v112, v86, s0
	v_lshl_add_u64 v[114:115], v[6:7], 0, v[114:115]
	global_store_short v[114:115], v112, off
	s_waitcnt lgkmcnt(0)
	s_barrier
	ds_read_b128 v[220:223], v42 offset:16384
	ds_read_b128 v[236:239], v42 offset:8192
	ds_read2st64_b32 v[108:109], v41 offset0:0 offset1:1
	ds_read_b128 v[244:247], v42 offset:20480
	ds_read_b128 v[228:231], v42 offset:4096
	ds_read_b128 v[100:103], v42 offset:0
	ds_read_b128 v[224:227], v42 offset:16640
	ds_read_b128 v[240:243], v42 offset:8448
	ds_read2st64_b32 v[110:111], v41 offset0:2 offset1:3
	ds_read_b128 v[248:251], v42 offset:20736
	ds_read_b128 v[232:235], v42 offset:4352
	global_load_ushort v70, v[46:47], off
	global_load_ushort v72, v[46:47], off offset:1024
	global_load_ushort v71, v[46:47], off offset:2048
	v_mad_u64_u32 v[46:47], s[6:7], v44, s29, v[4:5]
	v_add_u32_e32 v0, 1, v0
	v_mad_i32_i24 v47, v45, s29, v47
	v_lshl_add_u64 v[44:45], s[56:57], 0, v[0:1]
	v_max_i32_e32 v0, -2, v14
	v_mad_u64_u32 v[48:49], s[6:7], v44, s29, v[4:5]
	v_add_u32_e32 v0, 2, v0
	v_mad_i32_i24 v49, v45, s29, v49
	v_lshl_add_u64 v[44:45], s[56:57], 0, v[0:1]
	v_max_i32_e32 v0, -3, v14
	v_mad_u64_u32 v[50:51], s[6:7], v44, s29, v[4:5]
	v_add_u32_e32 v0, 3, v0
	v_mad_i32_i24 v51, v45, s29, v51
	v_lshl_add_u64 v[44:45], s[56:57], 0, v[0:1]
	v_ashrrev_i32_e32 v15, 31, v14
	v_mad_u64_u32 v[52:53], s[6:7], v44, s29, v[4:5]
	v_lshl_add_u64 v[80:81], s[56:57], 0, v[14:15]
	v_mad_i32_i24 v53, v45, s29, v53
	v_lshlrev_b64 v[44:45], 10, v[80:81]
	v_or_b32_e32 v86, 1, v80
	v_mov_b32_e32 v87, v81
	v_or_b32_e32 v92, 2, v80
	v_mov_b32_e32 v93, v81
	global_load_ushort v73, v[46:47], off
	global_load_ushort v69, v[46:47], off offset:1024
	global_load_ushort v76, v[46:47], off offset:2048
	global_load_ushort v77, v[48:49], off
	global_load_ushort v74, v[48:49], off offset:1024
	global_load_ushort v84, v[48:49], off offset:2048
	global_load_ushort v78, v[50:51], off offset:1024
	global_load_ushort v85, v[50:51], off offset:2048
	v_or_b32_e32 v44, v44, v83
	v_lshlrev_b64 v[48:49], 5, v[80:81]
	v_lshlrev_b64 v[88:89], 10, v[86:87]
	v_lshlrev_b64 v[86:87], 5, v[86:87]
	v_lshlrev_b64 v[94:95], 10, v[92:93]
	v_lshl_add_u64 v[46:47], s[0:1], 0, v[44:45]
	v_lshl_add_u64 v[44:45], s[24:25], 0, v[44:45]
	v_lshl_add_u64 v[48:49], s[58:59], 0, v[48:49]
	v_or_b32_e32 v88, v88, v83
	v_lshl_add_u64 v[86:87], s[58:59], 0, v[86:87]
	v_or_b32_e32 v94, v94, v83
	v_lshl_add_u64 v[90:91], s[0:1], 0, v[88:89]
	v_lshl_add_u64 v[88:89], s[24:25], 0, v[88:89]
	v_lshl_add_u64 v[96:97], s[0:1], 0, v[94:95]
	v_lshl_add_u64 v[94:95], s[24:25], 0, v[94:95]
	global_load_ushort v15, v[46:47], off
	global_load_ushort v43, v[44:45], off
	s_nop 0
	global_load_dword v44, v[48:49], off
	s_nop 0
	global_load_ushort v48, v[90:91], off
	global_load_ushort v49, v[88:89], off
	global_load_dword v46, v[86:87], off
	global_load_ushort v45, v[96:97], off
	global_load_ushort v47, v[94:95], off
	v_lshlrev_b64 v[86:87], 5, v[92:93]
	v_or_b32_e32 v80, 3, v80
	v_lshl_add_u64 v[88:89], s[58:59], 0, v[86:87]
	v_lshlrev_b64 v[86:87], 10, v[80:81]
	v_or_b32_e32 v86, v86, v83
	v_lshlrev_b64 v[80:81], 5, v[80:81]
	v_lshl_add_u64 v[90:91], s[0:1], 0, v[86:87]
	v_lshl_add_u64 v[92:93], s[24:25], 0, v[86:87]
	v_lshl_add_u64 v[80:81], s[58:59], 0, v[80:81]
	global_load_ushort v83, v[50:51], off
	global_load_ushort v0, v[52:53], off
	global_load_ushort v79, v[52:53], off offset:1024
	global_load_ushort v86, v[52:53], off offset:2048
	s_nop 0
	global_load_dword v52, v[88:89], off
	global_load_ushort v50, v[90:91], off
	global_load_ushort v51, v[92:93], off
	global_load_dword v53, v[80:81], off
	s_mov_b32 s6, 0
	v_mov_b32_e32 v87, 0
	v_mov_b32_e32 v75, v31
	v_mov_b32_e32 v80, v42
	v_mov_b32_e32 v81, v41
	s_waitcnt lgkmcnt(6)
	v_pk_mul_f32 v[88:89], v[12:13], v[220:221]
	v_pk_fma_f32 v[88:89], v[10:11], v[222:223], v[88:89]
	v_add_f32_e32 v90, v88, v89
	v_pk_mul_f32 v[92:93], v[108:109], v[236:237] op_sel_hi:[0,1]
	v_pk_mul_f32 v[94:95], v[108:109], v[238:239] op_sel_hi:[0,1]
	v_add_f32_dpp v90, v90, v90 row_ror:8 row_mask:0xf bank_mask:0xf bound_ctrl:1
	ds_read_b128 v[220:223], v42 offset:16896
	ds_read_b128 v[236:239], v42 offset:8704
	v_add_f32_dpp v90, v90, v90 row_ror:4 row_mask:0xf bank_mask:0xf bound_ctrl:1
	s_nop 1
	v_add_f32_dpp v90, v90, v90 row_ror:2 row_mask:0xf bank_mask:0xf bound_ctrl:1
	ds_read_b128 v[104:107], v42 offset:256
	s_nop 0
	v_add_f32_dpp v90, v90, v90 row_ror:1 row_mask:0xf bank_mask:0xf bound_ctrl:1
	v_pk_fma_f32 v[92:93], v[90:91], v[244:245], v[92:93] op_sel_hi:[0,1,1]
	v_pk_fma_f32 v[94:95], v[90:91], v[246:247], v[94:95] op_sel_hi:[0,1,1]
	ds_read_b128 v[244:247], v42 offset:20992
	v_pk_fma_f32 v[12:13], v[12:13], v[228:229], v[92:93]
	v_pk_fma_f32 v[10:11], v[10:11], v[230:231], v[94:95]
	ds_read_b128 v[228:231], v42 offset:4608
	s_waitcnt lgkmcnt(5)
	v_pk_mul_f32 v[88:89], v[12:13], v[224:225]
	v_pk_fma_f32 v[88:89], v[10:11], v[226:227], v[88:89]
	v_add_f32_e32 v90, v88, v89
	v_pk_mul_f32 v[92:93], v[108:109], v[240:241] op_sel:[1,0] op_sel_hi:[1,1]
	v_pk_mul_f32 v[94:95], v[108:109], v[242:243] op_sel:[1,0] op_sel_hi:[1,1]
	v_add_f32_dpp v90, v90, v90 row_ror:8 row_mask:0xf bank_mask:0xf bound_ctrl:1
	ds_read_b128 v[224:227], v42 offset:17152
	ds_read_b128 v[240:243], v42 offset:8960
	v_add_f32_dpp v90, v90, v90 row_ror:4 row_mask:0xf bank_mask:0xf bound_ctrl:1
	v_pk_mul_f32 v[100:101], v[12:13], v[100:101]
	v_pk_fma_f32 v[100:101], v[10:11], v[102:103], v[100:101]
	v_add_f32_dpp v90, v90, v90 row_ror:2 row_mask:0xf bank_mask:0xf bound_ctrl:1
	v_add_f32_e32 v96, v100, v101
	ds_read_b128 v[100:103], v42 offset:512
	v_add_f32_dpp v90, v90, v90 row_ror:1 row_mask:0xf bank_mask:0xf bound_ctrl:1
	ds_read2st64_b32 v[108:109], v41 offset0:4 offset1:5
	v_pk_fma_f32 v[92:93], v[90:91], v[248:249], v[92:93] op_sel_hi:[0,1,1]
	v_pk_fma_f32 v[94:95], v[90:91], v[250:251], v[94:95] op_sel_hi:[0,1,1]
	ds_read_b128 v[248:251], v42 offset:21248
	v_pk_fma_f32 v[12:13], v[12:13], v[232:233], v[92:93]
	v_pk_fma_f32 v[10:11], v[10:11], v[234:235], v[94:95]
	ds_read_b128 v[232:235], v42 offset:4864
	s_waitcnt lgkmcnt(6)
	v_pk_mul_f32 v[88:89], v[12:13], v[220:221]
	v_pk_fma_f32 v[88:89], v[10:11], v[222:223], v[88:89]
	v_add_f32_e32 v90, v88, v89
	v_pk_mul_f32 v[92:93], v[110:111], v[236:237] op_sel_hi:[0,1]
	v_pk_mul_f32 v[94:95], v[110:111], v[238:239] op_sel_hi:[0,1]
	v_add_f32_dpp v90, v90, v90 row_ror:8 row_mask:0xf bank_mask:0xf bound_ctrl:1
	ds_read_b128 v[220:223], v42 offset:17408
	ds_read_b128 v[236:239], v42 offset:9216
	v_add_f32_dpp v90, v90, v90 row_ror:4 row_mask:0xf bank_mask:0xf bound_ctrl:1
	v_pk_mul_f32 v[104:105], v[12:13], v[104:105]
	v_pk_fma_f32 v[104:105], v[10:11], v[106:107], v[104:105]
	v_add_f32_dpp v90, v90, v90 row_ror:2 row_mask:0xf bank_mask:0xf bound_ctrl:1
	v_add_f32_e32 v97, v104, v105
	ds_read_b128 v[104:107], v42 offset:768
	v_add_f32_dpp v90, v90, v90 row_ror:1 row_mask:0xf bank_mask:0xf bound_ctrl:1
	v_pk_fma_f32 v[92:93], v[90:91], v[244:245], v[92:93] op_sel_hi:[0,1,1]
	v_pk_fma_f32 v[94:95], v[90:91], v[246:247], v[94:95] op_sel_hi:[0,1,1]
	ds_read_b128 v[244:247], v42 offset:21504
	v_pk_fma_f32 v[12:13], v[12:13], v[228:229], v[92:93]
	v_pk_fma_f32 v[10:11], v[10:11], v[230:231], v[94:95]
	ds_read_b128 v[228:231], v42 offset:5120
	s_waitcnt lgkmcnt(5)
	v_pk_mul_f32 v[88:89], v[12:13], v[224:225]
	v_pk_fma_f32 v[88:89], v[10:11], v[226:227], v[88:89]
	v_add_f32_e32 v90, v88, v89
	v_pk_mul_f32 v[92:93], v[110:111], v[240:241] op_sel:[1,0] op_sel_hi:[1,1]
	v_pk_mul_f32 v[94:95], v[110:111], v[242:243] op_sel:[1,0] op_sel_hi:[1,1]
	v_add_f32_dpp v90, v90, v90 row_ror:8 row_mask:0xf bank_mask:0xf bound_ctrl:1
	ds_read_b128 v[224:227], v42 offset:17664
	ds_read_b128 v[240:243], v42 offset:9472
	v_add_f32_dpp v90, v90, v90 row_ror:4 row_mask:0xf bank_mask:0xf bound_ctrl:1
	v_pk_mul_f32 v[100:101], v[12:13], v[100:101]
	v_pk_fma_f32 v[100:101], v[10:11], v[102:103], v[100:101]
	v_add_f32_dpp v90, v90, v90 row_ror:2 row_mask:0xf bank_mask:0xf bound_ctrl:1
	v_add_f32_e32 v98, v100, v101
	ds_read_b128 v[100:103], v42 offset:1024
	v_add_f32_dpp v90, v90, v90 row_ror:1 row_mask:0xf bank_mask:0xf bound_ctrl:1
	ds_read2st64_b32 v[110:111], v41 offset0:6 offset1:7
	v_pk_fma_f32 v[92:93], v[90:91], v[248:249], v[92:93] op_sel_hi:[0,1,1]
	v_pk_fma_f32 v[94:95], v[90:91], v[250:251], v[94:95] op_sel_hi:[0,1,1]
	ds_read_b128 v[248:251], v42 offset:21760
	v_pk_fma_f32 v[12:13], v[12:13], v[232:233], v[92:93]
	v_pk_fma_f32 v[10:11], v[10:11], v[234:235], v[94:95]
	ds_read_b128 v[232:235], v42 offset:5376
	s_waitcnt lgkmcnt(6)
	v_pk_mul_f32 v[88:89], v[12:13], v[220:221]
	v_pk_fma_f32 v[88:89], v[10:11], v[222:223], v[88:89]
	v_add_f32_e32 v90, v88, v89
	v_pk_mul_f32 v[92:93], v[108:109], v[236:237] op_sel_hi:[0,1]
	v_pk_mul_f32 v[94:95], v[108:109], v[238:239] op_sel_hi:[0,1]
	v_add_f32_dpp v90, v90, v90 row_ror:8 row_mask:0xf bank_mask:0xf bound_ctrl:1
	ds_read_b128 v[220:223], v42 offset:17920
	ds_read_b128 v[236:239], v42 offset:9728
	v_add_f32_dpp v90, v90, v90 row_ror:4 row_mask:0xf bank_mask:0xf bound_ctrl:1
	v_pk_mul_f32 v[104:105], v[12:13], v[104:105]
	v_pk_fma_f32 v[104:105], v[10:11], v[106:107], v[104:105]
	v_add_f32_dpp v90, v90, v90 row_ror:2 row_mask:0xf bank_mask:0xf bound_ctrl:1
	v_add_f32_e32 v99, v104, v105
	ds_read_b128 v[104:107], v42 offset:1280
	v_add_f32_dpp v90, v90, v90 row_ror:1 row_mask:0xf bank_mask:0xf bound_ctrl:1
	v_pk_fma_f32 v[92:93], v[90:91], v[244:245], v[92:93] op_sel_hi:[0,1,1]
	v_pk_fma_f32 v[94:95], v[90:91], v[246:247], v[94:95] op_sel_hi:[0,1,1]
	ds_read_b128 v[244:247], v42 offset:22016
	v_pk_fma_f32 v[12:13], v[12:13], v[228:229], v[92:93]
	v_pk_fma_f32 v[10:11], v[10:11], v[230:231], v[94:95]
	ds_read_b128 v[228:231], v42 offset:5632
	s_waitcnt lgkmcnt(5)
	v_pk_mul_f32 v[88:89], v[12:13], v[224:225]
	v_pk_fma_f32 v[88:89], v[10:11], v[226:227], v[88:89]
	v_add_f32_e32 v90, v88, v89
	v_pk_mul_f32 v[92:93], v[108:109], v[240:241] op_sel:[1,0] op_sel_hi:[1,1]
	v_pk_mul_f32 v[94:95], v[108:109], v[242:243] op_sel:[1,0] op_sel_hi:[1,1]
	v_add_f32_dpp v90, v90, v90 row_ror:8 row_mask:0xf bank_mask:0xf bound_ctrl:1
	ds_read_b128 v[224:227], v42 offset:18176
	ds_read_b128 v[240:243], v42 offset:9984
	v_add_f32_dpp v90, v90, v90 row_ror:4 row_mask:0xf bank_mask:0xf bound_ctrl:1
	v_pk_mul_f32 v[100:101], v[12:13], v[100:101]
	v_pk_fma_f32 v[100:101], v[10:11], v[102:103], v[100:101]
	v_add_f32_dpp v90, v90, v90 row_ror:2 row_mask:0xf bank_mask:0xf bound_ctrl:1
	v_add_f32_e32 v87, v100, v101
	ds_read_b128 v[100:103], v42 offset:1536
	v_add_f32_dpp v90, v90, v90 row_ror:1 row_mask:0xf bank_mask:0xf bound_ctrl:1
	ds_read2st64_b32 v[108:109], v41 offset0:8 offset1:9
	v_pk_fma_f32 v[92:93], v[90:91], v[248:249], v[92:93] op_sel_hi:[0,1,1]
	v_pk_fma_f32 v[94:95], v[90:91], v[250:251], v[94:95] op_sel_hi:[0,1,1]
	ds_read_b128 v[248:251], v42 offset:22272
	v_pk_fma_f32 v[12:13], v[12:13], v[232:233], v[92:93]
	v_pk_fma_f32 v[10:11], v[10:11], v[234:235], v[94:95]
	ds_read_b128 v[232:235], v42 offset:5888
	s_waitcnt lgkmcnt(6)
	v_pk_mul_f32 v[88:89], v[12:13], v[220:221]
	v_pk_fma_f32 v[88:89], v[10:11], v[222:223], v[88:89]
	v_add_f32_e32 v90, v88, v89
	v_pk_mul_f32 v[92:93], v[110:111], v[236:237] op_sel_hi:[0,1]
	v_pk_mul_f32 v[94:95], v[110:111], v[238:239] op_sel_hi:[0,1]
	v_add_f32_dpp v90, v90, v90 row_ror:8 row_mask:0xf bank_mask:0xf bound_ctrl:1
	ds_read_b128 v[220:223], v42 offset:18432
	ds_read_b128 v[236:239], v42 offset:10240
	v_add_f32_dpp v90, v90, v90 row_ror:4 row_mask:0xf bank_mask:0xf bound_ctrl:1
	v_pk_mul_f32 v[104:105], v[12:13], v[104:105]
	v_pk_fma_f32 v[104:105], v[10:11], v[106:107], v[104:105]
	v_add_f32_dpp v90, v90, v90 row_ror:2 row_mask:0xf bank_mask:0xf bound_ctrl:1
	v_add_f32_e32 v217, v104, v105
	ds_read_b128 v[104:107], v42 offset:1792
	v_add_f32_dpp v90, v90, v90 row_ror:1 row_mask:0xf bank_mask:0xf bound_ctrl:1
	v_pk_fma_f32 v[92:93], v[90:91], v[244:245], v[92:93] op_sel_hi:[0,1,1]
	v_pk_fma_f32 v[94:95], v[90:91], v[246:247], v[94:95] op_sel_hi:[0,1,1]
	ds_read_b128 v[244:247], v42 offset:22528
	v_pk_fma_f32 v[12:13], v[12:13], v[228:229], v[92:93]
	v_pk_fma_f32 v[10:11], v[10:11], v[230:231], v[94:95]
	ds_read_b128 v[228:231], v42 offset:6144
	s_waitcnt lgkmcnt(5)
	v_pk_mul_f32 v[88:89], v[12:13], v[224:225]
	v_pk_fma_f32 v[88:89], v[10:11], v[226:227], v[88:89]
	v_add_f32_e32 v90, v88, v89
	v_pk_mul_f32 v[92:93], v[110:111], v[240:241] op_sel:[1,0] op_sel_hi:[1,1]
	v_pk_mul_f32 v[94:95], v[110:111], v[242:243] op_sel:[1,0] op_sel_hi:[1,1]
	v_add_f32_dpp v90, v90, v90 row_ror:8 row_mask:0xf bank_mask:0xf bound_ctrl:1
	ds_read_b128 v[224:227], v42 offset:18688
	ds_read_b128 v[240:243], v42 offset:10496
	v_add_f32_dpp v90, v90, v90 row_ror:4 row_mask:0xf bank_mask:0xf bound_ctrl:1
	v_pk_mul_f32 v[100:101], v[12:13], v[100:101]
	v_pk_fma_f32 v[100:101], v[10:11], v[102:103], v[100:101]
	v_add_f32_dpp v90, v90, v90 row_ror:2 row_mask:0xf bank_mask:0xf bound_ctrl:1
	v_add_f32_e32 v218, v100, v101
	ds_read_b128 v[100:103], v42 offset:2048
	v_add_f32_dpp v90, v90, v90 row_ror:1 row_mask:0xf bank_mask:0xf bound_ctrl:1
	ds_read2st64_b32 v[110:111], v41 offset0:10 offset1:11
	v_pk_fma_f32 v[92:93], v[90:91], v[248:249], v[92:93] op_sel_hi:[0,1,1]
	v_pk_fma_f32 v[94:95], v[90:91], v[250:251], v[94:95] op_sel_hi:[0,1,1]
	ds_read_b128 v[248:251], v42 offset:22784
	v_pk_fma_f32 v[12:13], v[12:13], v[232:233], v[92:93]
	v_pk_fma_f32 v[10:11], v[10:11], v[234:235], v[94:95]
	ds_read_b128 v[232:235], v42 offset:6400
	s_waitcnt lgkmcnt(6)
	v_pk_mul_f32 v[88:89], v[12:13], v[220:221]
	v_pk_fma_f32 v[88:89], v[10:11], v[222:223], v[88:89]
	v_add_f32_e32 v90, v88, v89
	v_pk_mul_f32 v[92:93], v[108:109], v[236:237] op_sel_hi:[0,1]
	v_pk_mul_f32 v[94:95], v[108:109], v[238:239] op_sel_hi:[0,1]
	v_add_f32_dpp v90, v90, v90 row_ror:8 row_mask:0xf bank_mask:0xf bound_ctrl:1
	ds_read_b128 v[220:223], v42 offset:18944
	ds_read_b128 v[236:239], v42 offset:10752
	v_add_f32_dpp v90, v90, v90 row_ror:4 row_mask:0xf bank_mask:0xf bound_ctrl:1
	v_pk_mul_f32 v[104:105], v[12:13], v[104:105]
	v_pk_fma_f32 v[104:105], v[10:11], v[106:107], v[104:105]
	v_add_f32_dpp v90, v90, v90 row_ror:2 row_mask:0xf bank_mask:0xf bound_ctrl:1
	v_add_f32_e32 v219, v104, v105
	ds_read_b128 v[104:107], v42 offset:2304
	v_add_f32_dpp v90, v90, v90 row_ror:1 row_mask:0xf bank_mask:0xf bound_ctrl:1
	v_pk_fma_f32 v[92:93], v[90:91], v[244:245], v[92:93] op_sel_hi:[0,1,1]
	v_pk_fma_f32 v[94:95], v[90:91], v[246:247], v[94:95] op_sel_hi:[0,1,1]
	ds_read_b128 v[244:247], v42 offset:23040
	v_pk_fma_f32 v[12:13], v[12:13], v[228:229], v[92:93]
	v_pk_fma_f32 v[10:11], v[10:11], v[230:231], v[94:95]
	ds_read_b128 v[228:231], v42 offset:6656
	s_waitcnt lgkmcnt(5)
	v_pk_mul_f32 v[88:89], v[12:13], v[224:225]
	v_pk_fma_f32 v[88:89], v[10:11], v[226:227], v[88:89]
	v_add_f32_e32 v90, v88, v89
	v_pk_mul_f32 v[92:93], v[108:109], v[240:241] op_sel:[1,0] op_sel_hi:[1,1]
	v_pk_mul_f32 v[94:95], v[108:109], v[242:243] op_sel:[1,0] op_sel_hi:[1,1]
	v_add_f32_dpp v90, v90, v90 row_ror:8 row_mask:0xf bank_mask:0xf bound_ctrl:1
	ds_read_b128 v[224:227], v42 offset:19200
	ds_read_b128 v[240:243], v42 offset:11008
	v_add_f32_dpp v90, v90, v90 row_ror:4 row_mask:0xf bank_mask:0xf bound_ctrl:1
	v_pk_mul_f32 v[100:101], v[12:13], v[100:101]
	v_pk_fma_f32 v[100:101], v[10:11], v[102:103], v[100:101]
	v_add_f32_dpp v90, v90, v90 row_ror:2 row_mask:0xf bank_mask:0xf bound_ctrl:1
	v_add_f32_e32 v187, v100, v101
	ds_read_b128 v[100:103], v42 offset:2560
	v_add_f32_dpp v90, v90, v90 row_ror:1 row_mask:0xf bank_mask:0xf bound_ctrl:1
	ds_read2st64_b32 v[108:109], v41 offset0:12 offset1:13
	v_pk_fma_f32 v[92:93], v[90:91], v[248:249], v[92:93] op_sel_hi:[0,1,1]
	v_pk_fma_f32 v[94:95], v[90:91], v[250:251], v[94:95] op_sel_hi:[0,1,1]
	ds_read_b128 v[248:251], v42 offset:23296
	v_pk_fma_f32 v[12:13], v[12:13], v[232:233], v[92:93]
	v_pk_fma_f32 v[10:11], v[10:11], v[234:235], v[94:95]
	ds_read_b128 v[232:235], v42 offset:6912
	s_waitcnt lgkmcnt(6)
	v_pk_mul_f32 v[88:89], v[12:13], v[220:221]
	v_pk_fma_f32 v[88:89], v[10:11], v[222:223], v[88:89]
	v_add_f32_e32 v90, v88, v89
	v_pk_mul_f32 v[92:93], v[110:111], v[236:237] op_sel_hi:[0,1]
	v_pk_mul_f32 v[94:95], v[110:111], v[238:239] op_sel_hi:[0,1]
	v_add_f32_dpp v90, v90, v90 row_ror:8 row_mask:0xf bank_mask:0xf bound_ctrl:1
	ds_read_b128 v[220:223], v42 offset:19456
	ds_read_b128 v[236:239], v42 offset:11264
	v_add_f32_dpp v90, v90, v90 row_ror:4 row_mask:0xf bank_mask:0xf bound_ctrl:1
	v_pk_mul_f32 v[104:105], v[12:13], v[104:105]
	v_pk_fma_f32 v[104:105], v[10:11], v[106:107], v[104:105]
	v_add_f32_dpp v90, v90, v90 row_ror:2 row_mask:0xf bank_mask:0xf bound_ctrl:1
	v_add_f32_e32 v190, v104, v105
	ds_read_b128 v[104:107], v42 offset:2816
	v_add_f32_dpp v90, v90, v90 row_ror:1 row_mask:0xf bank_mask:0xf bound_ctrl:1
	v_pk_fma_f32 v[92:93], v[90:91], v[244:245], v[92:93] op_sel_hi:[0,1,1]
	v_pk_fma_f32 v[94:95], v[90:91], v[246:247], v[94:95] op_sel_hi:[0,1,1]
	ds_read_b128 v[244:247], v42 offset:23552
	v_pk_fma_f32 v[12:13], v[12:13], v[228:229], v[92:93]
	v_pk_fma_f32 v[10:11], v[10:11], v[230:231], v[94:95]
	ds_read_b128 v[228:231], v42 offset:7168
	s_waitcnt lgkmcnt(5)
	v_pk_mul_f32 v[88:89], v[12:13], v[224:225]
	v_pk_fma_f32 v[88:89], v[10:11], v[226:227], v[88:89]
	v_add_f32_e32 v90, v88, v89
	v_pk_mul_f32 v[92:93], v[110:111], v[240:241] op_sel:[1,0] op_sel_hi:[1,1]
	v_pk_mul_f32 v[94:95], v[110:111], v[242:243] op_sel:[1,0] op_sel_hi:[1,1]
	v_add_f32_dpp v90, v90, v90 row_ror:8 row_mask:0xf bank_mask:0xf bound_ctrl:1
	ds_read_b128 v[224:227], v42 offset:19712
	ds_read_b128 v[240:243], v42 offset:11520
	v_add_f32_dpp v90, v90, v90 row_ror:4 row_mask:0xf bank_mask:0xf bound_ctrl:1
	v_pk_mul_f32 v[100:101], v[12:13], v[100:101]
	v_pk_fma_f32 v[100:101], v[10:11], v[102:103], v[100:101]
	v_add_f32_dpp v90, v90, v90 row_ror:2 row_mask:0xf bank_mask:0xf bound_ctrl:1
	v_add_f32_e32 v191, v100, v101
	ds_read_b128 v[100:103], v42 offset:3072
	v_add_f32_dpp v90, v90, v90 row_ror:1 row_mask:0xf bank_mask:0xf bound_ctrl:1
	ds_read2st64_b32 v[110:111], v41 offset0:14 offset1:15
	v_pk_fma_f32 v[92:93], v[90:91], v[248:249], v[92:93] op_sel_hi:[0,1,1]
	v_pk_fma_f32 v[94:95], v[90:91], v[250:251], v[94:95] op_sel_hi:[0,1,1]
	ds_read_b128 v[248:251], v42 offset:23808
	v_pk_fma_f32 v[12:13], v[12:13], v[232:233], v[92:93]
	v_pk_fma_f32 v[10:11], v[10:11], v[234:235], v[94:95]
	ds_read_b128 v[232:235], v42 offset:7424
	s_waitcnt lgkmcnt(6)
	v_pk_mul_f32 v[88:89], v[12:13], v[220:221]
	v_pk_fma_f32 v[88:89], v[10:11], v[222:223], v[88:89]
	v_add_f32_e32 v90, v88, v89
	v_pk_mul_f32 v[92:93], v[108:109], v[236:237] op_sel_hi:[0,1]
	v_pk_mul_f32 v[94:95], v[108:109], v[238:239] op_sel_hi:[0,1]
	v_add_f32_dpp v90, v90, v90 row_ror:8 row_mask:0xf bank_mask:0xf bound_ctrl:1
	ds_read_b128 v[220:223], v42 offset:19968
	ds_read_b128 v[236:239], v42 offset:11776
	v_add_f32_dpp v90, v90, v90 row_ror:4 row_mask:0xf bank_mask:0xf bound_ctrl:1
	v_pk_mul_f32 v[104:105], v[12:13], v[104:105]
	v_pk_fma_f32 v[104:105], v[10:11], v[106:107], v[104:105]
	v_add_f32_dpp v90, v90, v90 row_ror:2 row_mask:0xf bank_mask:0xf bound_ctrl:1
	v_add_f32_e32 v200, v104, v105
	ds_read_b128 v[104:107], v42 offset:3328
	v_add_f32_dpp v90, v90, v90 row_ror:1 row_mask:0xf bank_mask:0xf bound_ctrl:1
	v_pk_fma_f32 v[92:93], v[90:91], v[244:245], v[92:93] op_sel_hi:[0,1,1]
	v_pk_fma_f32 v[94:95], v[90:91], v[246:247], v[94:95] op_sel_hi:[0,1,1]
	ds_read_b128 v[244:247], v42 offset:24064
	v_pk_fma_f32 v[12:13], v[12:13], v[228:229], v[92:93]
	v_pk_fma_f32 v[10:11], v[10:11], v[230:231], v[94:95]
	ds_read_b128 v[228:231], v42 offset:7680
	s_waitcnt lgkmcnt(5)
	v_pk_mul_f32 v[88:89], v[12:13], v[224:225]
	v_pk_fma_f32 v[88:89], v[10:11], v[226:227], v[88:89]
	v_add_f32_e32 v90, v88, v89
	v_pk_mul_f32 v[92:93], v[108:109], v[240:241] op_sel:[1,0] op_sel_hi:[1,1]
	v_pk_mul_f32 v[94:95], v[108:109], v[242:243] op_sel:[1,0] op_sel_hi:[1,1]
	v_add_f32_dpp v90, v90, v90 row_ror:8 row_mask:0xf bank_mask:0xf bound_ctrl:1
	ds_read_b128 v[224:227], v42 offset:20224
	ds_read_b128 v[240:243], v42 offset:12032
	v_add_f32_dpp v90, v90, v90 row_ror:4 row_mask:0xf bank_mask:0xf bound_ctrl:1
	v_pk_mul_f32 v[100:101], v[12:13], v[100:101]
	v_pk_fma_f32 v[100:101], v[10:11], v[102:103], v[100:101]
	v_add_f32_dpp v90, v90, v90 row_ror:2 row_mask:0xf bank_mask:0xf bound_ctrl:1
	v_add_f32_e32 v75, v100, v101
	ds_read_b128 v[100:103], v42 offset:3584
	v_add_f32_dpp v90, v90, v90 row_ror:1 row_mask:0xf bank_mask:0xf bound_ctrl:1
	v_pk_fma_f32 v[92:93], v[90:91], v[248:249], v[92:93] op_sel_hi:[0,1,1]
	v_pk_fma_f32 v[94:95], v[90:91], v[250:251], v[94:95] op_sel_hi:[0,1,1]
	ds_read_b128 v[248:251], v42 offset:24320
	v_pk_fma_f32 v[12:13], v[12:13], v[232:233], v[92:93]
	v_pk_fma_f32 v[10:11], v[10:11], v[234:235], v[94:95]
	ds_read_b128 v[232:235], v42 offset:7936
	s_waitcnt lgkmcnt(5)
	v_pk_mul_f32 v[88:89], v[12:13], v[220:221]
	v_pk_fma_f32 v[88:89], v[10:11], v[222:223], v[88:89]
	v_add_f32_e32 v90, v88, v89
	v_pk_mul_f32 v[92:93], v[110:111], v[236:237] op_sel_hi:[0,1]
	v_pk_mul_f32 v[94:95], v[110:111], v[238:239] op_sel_hi:[0,1]
	v_add_f32_dpp v90, v90, v90 row_ror:8 row_mask:0xf bank_mask:0xf bound_ctrl:1
	s_nop 1
	v_add_f32_dpp v90, v90, v90 row_ror:4 row_mask:0xf bank_mask:0xf bound_ctrl:1
	v_pk_mul_f32 v[104:105], v[12:13], v[104:105]
	v_pk_fma_f32 v[104:105], v[10:11], v[106:107], v[104:105]
	v_add_f32_dpp v90, v90, v90 row_ror:2 row_mask:0xf bank_mask:0xf bound_ctrl:1
	v_add_f32_e32 v80, v104, v105
	ds_read_b128 v[104:107], v42 offset:3840
	v_add_f32_dpp v90, v90, v90 row_ror:1 row_mask:0xf bank_mask:0xf bound_ctrl:1
	v_pk_fma_f32 v[92:93], v[90:91], v[244:245], v[92:93] op_sel_hi:[0,1,1]
	v_pk_fma_f32 v[94:95], v[90:91], v[246:247], v[94:95] op_sel_hi:[0,1,1]
	v_pk_fma_f32 v[12:13], v[12:13], v[228:229], v[92:93]
	v_pk_fma_f32 v[10:11], v[10:11], v[230:231], v[94:95]
	s_waitcnt lgkmcnt(1)
	v_pk_mul_f32 v[88:89], v[12:13], v[224:225]
	v_pk_fma_f32 v[88:89], v[10:11], v[226:227], v[88:89]
	v_add_f32_e32 v90, v88, v89
	v_pk_mul_f32 v[92:93], v[110:111], v[240:241] op_sel:[1,0] op_sel_hi:[1,1]
	v_pk_mul_f32 v[94:95], v[110:111], v[242:243] op_sel:[1,0] op_sel_hi:[1,1]
	v_add_f32_dpp v90, v90, v90 row_ror:8 row_mask:0xf bank_mask:0xf bound_ctrl:1
	s_nop 1
	v_add_f32_dpp v90, v90, v90 row_ror:4 row_mask:0xf bank_mask:0xf bound_ctrl:1
	v_pk_mul_f32 v[100:101], v[12:13], v[100:101]
	v_pk_fma_f32 v[100:101], v[10:11], v[102:103], v[100:101]
	v_add_f32_dpp v90, v90, v90 row_ror:2 row_mask:0xf bank_mask:0xf bound_ctrl:1
	v_add_f32_e32 v81, v100, v101
	s_nop 0
	v_add_f32_dpp v90, v90, v90 row_ror:1 row_mask:0xf bank_mask:0xf bound_ctrl:1
	v_pk_fma_f32 v[92:93], v[90:91], v[248:249], v[92:93] op_sel_hi:[0,1,1]
	v_pk_fma_f32 v[94:95], v[90:91], v[250:251], v[94:95] op_sel_hi:[0,1,1]
	v_pk_fma_f32 v[12:13], v[12:13], v[232:233], v[92:93]
	v_pk_fma_f32 v[10:11], v[10:11], v[234:235], v[94:95]
	s_waitcnt lgkmcnt(0)
	v_pk_mul_f32 v[104:105], v[12:13], v[104:105]
	v_pk_fma_f32 v[104:105], v[10:11], v[106:107], v[104:105]
	v_add_f32_dpp v96, v96, v96 row_mirror row_mask:0xf bank_mask:0x3
	v_add_f32_dpp v96, v187, v187 row_mirror row_mask:0xf bank_mask:0xc
	v_add_f32_e32 v82, v104, v105
	v_add_f32_dpp v97, v97, v97 row_mirror row_mask:0xf bank_mask:0x3
	v_add_f32_dpp v97, v190, v190 row_mirror row_mask:0xf bank_mask:0xc
	v_add_f32_dpp v98, v98, v98 row_mirror row_mask:0xf bank_mask:0x3
	v_add_f32_dpp v98, v191, v191 row_mirror row_mask:0xf bank_mask:0xc
	v_add_f32_dpp v99, v99, v99 row_mirror row_mask:0xf bank_mask:0x3
	v_add_f32_dpp v99, v200, v200 row_mirror row_mask:0xf bank_mask:0xc
	v_add_f32_dpp v87, v87, v87 row_mirror row_mask:0xf bank_mask:0x3
	v_add_f32_dpp v87, v75, v75 row_mirror row_mask:0xf bank_mask:0xc
	v_add_f32_dpp v217, v217, v217 row_mirror row_mask:0xf bank_mask:0x3
	v_add_f32_dpp v217, v80, v80 row_mirror row_mask:0xf bank_mask:0xc
	v_add_f32_dpp v218, v218, v218 row_mirror row_mask:0xf bank_mask:0x3
	v_add_f32_dpp v218, v81, v81 row_mirror row_mask:0xf bank_mask:0xc
	v_add_f32_dpp v219, v219, v219 row_mirror row_mask:0xf bank_mask:0x3
	v_add_f32_dpp v219, v82, v82 row_mirror row_mask:0xf bank_mask:0xc
	v_add_f32_dpp v96, v96, v96 row_half_mirror row_mask:0xf bank_mask:0x5
	v_add_f32_dpp v96, v87, v87 row_half_mirror row_mask:0xf bank_mask:0xa
	v_add_f32_dpp v97, v97, v97 row_half_mirror row_mask:0xf bank_mask:0x5
	v_add_f32_dpp v97, v217, v217 row_half_mirror row_mask:0xf bank_mask:0xa
	v_add_f32_dpp v98, v98, v98 row_half_mirror row_mask:0xf bank_mask:0x5
	v_add_f32_dpp v98, v218, v218 row_half_mirror row_mask:0xf bank_mask:0xa
	v_add_f32_dpp v99, v99, v99 row_half_mirror row_mask:0xf bank_mask:0x5
	v_add_f32_dpp v99, v219, v219 row_half_mirror row_mask:0xf bank_mask:0xa
	s_mov_b32 vcc_lo, 0xcccccccc
	s_mov_b32 vcc_hi, 0xcccccccc
	v_cndmask_b32_e32 v187, v96, v98, vcc
	v_cndmask_b32_e32 v190, v98, v96, vcc
	v_cndmask_b32_e32 v200, v99, v97, vcc
	v_cndmask_b32_e32 v191, v97, v99, vcc
	v_add_f32_dpp v75, v190, v187 quad_perm:[2,3,0,1] row_mask:0xf bank_mask:0xf bound_ctrl:1
	v_add_f32_dpp v80, v200, v191 quad_perm:[2,3,0,1] row_mask:0xf bank_mask:0xf bound_ctrl:1
	s_mov_b32 vcc_lo, 0xaaaaaaaa
	s_mov_b32 vcc_hi, 0xaaaaaaaa
	v_cndmask_b32_e32 v81, v75, v80, vcc
	v_cndmask_b32_e32 v82, v80, v75, vcc
	s_nop 1
	v_add_f32_dpp v87, v82, v81 quad_perm:[1,0,3,2] row_mask:0xf bank_mask:0xf bound_ctrl:1
	s_waitcnt vmcnt(7)
	v_cmp_gt_i32_e32 vcc, 0, v8
	v_cmp_gt_i32_e64 s[38:39], -2, v8
	v_cmp_gt_i32_e64 s[40:41], -3, v8
	v_cmp_gt_i32_e64 s[42:43], 0, v14
	v_cmp_gt_i32_e64 s[44:45], -2, v14
	v_cmp_gt_i32_e64 s[46:47], 1, v8
	v_cmp_gt_i32_e64 s[48:49], -1, v8
	v_cmp_gt_i32_e64 s[52:53], -1, v14
	v_lshl_or_b32 v8, s5, 4, v31
	v_cndmask_b32_e64 v82, v73, 0, s[42:43]
	v_cndmask_b32_e64 v81, v76, 0, s[42:43]
	v_cndmask_b32_e64 v76, v77, 0, s[52:53]
	v_cndmask_b32_e64 v77, v84, 0, s[52:53]
	v_cndmask_b32_e64 v73, v85, 0, s[44:45]
	v_or_b32_e32 v84, s56, v8
	v_mov_b32_e32 v85, s57
	v_cmp_gt_i32_e64 s[50:51], 1, v14
	v_cmp_gt_i32_e64 s[54:55], -3, v14
	v_lshlrev_b64 v[84:85], 10, v[84:85]
	s_add_i32 s5, s4, 2
	v_cndmask_b32_e64 v89, v59, 0, vcc
	v_cndmask_b32_e64 v88, v60, 0, vcc
	v_cndmask_b32_e64 v60, v67, 0, s[38:39]
	v_cndmask_b32_e64 v59, v68, 0, s[40:41]
	v_cndmask_b32_e64 v64, v64, 0, s[38:39]
	v_cndmask_b32_e64 v75, v69, 0, s[42:43]
	v_cndmask_b32_e64 v69, v78, 0, s[44:45]
	v_cndmask_b32_e64 v67, v57, 0, s[46:47]
	v_cndmask_b32_e64 v57, v62, 0, s[48:49]
	v_cndmask_b32_e64 v62, v55, 0, s[46:47]
	v_cndmask_b32_e64 v61, v61, 0, s[48:49]
	v_cndmask_b32_e64 v55, v66, 0, s[40:41]
	v_cndmask_b32_e64 v78, v72, 0, s[50:51]
	v_cndmask_b32_e64 v74, v74, 0, s[52:53]
	s_waitcnt vmcnt(5)
	v_cndmask_b32_e64 v14, v79, 0, s[54:55]
	v_cndmask_b32_e64 v66, v54, 0, s[46:47]
	v_cndmask_b32_e64 v68, v56, 0, vcc
	v_cndmask_b32_e64 v58, v58, 0, s[48:49]
	v_cndmask_b32_e64 v56, v63, 0, s[38:39]
	v_cndmask_b32_e64 v54, v65, 0, s[40:41]
	v_cndmask_b32_e64 v80, v70, 0, s[50:51]
	v_cndmask_b32_e64 v79, v71, 0, s[50:51]
	v_cndmask_b32_e64 v72, v83, 0, s[44:45]
	v_cndmask_b32_e64 v70, v0, 0, s[54:55]
	s_waitcnt vmcnt(4)
	v_cndmask_b32_e64 v71, v86, 0, s[54:55]
	v_cvt_pk_bf16_f32 v0, v87, s0
	v_lshl_add_u64 v[84:85], v[6:7], 0, v[84:85]
	s_cmpk_lt_u32 s4, 0xfe
	s_mov_b32 s4, s5
	global_store_short v[84:85], v0, off
	s_cbranch_scc1 .LBB0_334
	s_setprio 0
	v_mov_b32_e32 v0, v133
	s_barrier
	s_nop 0
	v_cmp_eq_u32_e32 vcc, 0, v0
	s_and_saveexec_b64 s[4:5], vcc
	s_cbranch_execnz .LBB0_329
	s_branch .LBB0_332
